# baseline (speedup 1.0000x reference)
; #define LAS __attribute__((address_space(3)))
; __global__ void __launch_bounds__(NWAVES * 64) fwd_kernel(Args a_) {
;     extern __shared__ __attribute__((aligned(16))) unsigned char lds_raw[];
;     LAS unsigned char* lds = (LAS unsigned char*)lds_raw;
;     typedef const __attribute__((address_space(4))) Args* KArgs;
;     const KArgs ap0 = (KArgs)__builtin_amdgcn_kernarg_segment_ptr();
;     volatile LAS unsigned* MISC = (volatile LAS unsigned*)(lds + MISC_OFF);
;     if (threadIdx.x < 32) MISC[threadIdx.x] = 0u;
;     __syncthreads();
;     const int ph_lo = a_.ph_lo, ph_hi = a_.ph_hi;
;     ...
;     if (ph_hi - ph_lo > 1) (void)xcd_barrier_post((unsigned*)(a_.ws + WS_BAR), MISC + 8);
;     int ph = ph_lo;
;     if (ph == 0 && ph < ph_hi) {
_Z10fwd_kernel4Args:
	s_load_dwordx4 s[16:19], s[0:1], 0x78
	s_mov_b32 s101, 0
	v_and_b32_e32 v168, 0x3ff, v0
	s_mov_b64 s[90:91], s[0:1]
	v_cmp_gt_u32_e32 vcc, 32, v168
	s_and_saveexec_b64 s[4:5], vcc
	v_lshl_add_u32 v1, v168, 2, 0
	v_add_u32_e32 v1, 0x20140, v1
	v_mov_b32_e32 v2, 0
	ds_write_b32 v1, v2
	s_or_b64 exec, exec, s[4:5]
	s_waitcnt lgkmcnt(0)
	s_sub_i32 s0, s19, s18
	s_cmp_lt_i32 s0, 2
	v_cmp_eq_u32_e32 vcc, 0, v168
	s_barrier
	s_cbranch_scc0 .LBB0_5
	s_cmp_lg_u32 s18, 0
	s_mov_b32 s1, 0
	s_cbranch_scc0 .LBB0_9

; #define LAS __attribute__((address_space(3)))
; __device__ __forceinline__ void p0_prologue(const Args& a, LAS unsigned char* lds, int tid, int lane, int wave) {
;     LAS float* scr = (LAS float*)(lds + wave * 16384);
;     const int G = gridDim.x, gw = blockIdx.x * NWAVES + wave, NGW = G * NWAVES;
;     unsigned char* ws = a.ws;
;     bf16* W1T = (bf16*)(ws + WS_W1T); bf16* W2T = (bf16*)(ws + WS_W2T); bf16* WM = (bf16*)(ws + WS_WM); bf16* XB = (bf16*)(ws + WS_XB); float* ROWSS = (float*)(ws + WS_ROWSS);
;     constexpr int I1 = (DM / 64) * (NCOLS / 32), I2 = (MIXW / 64) * (DM / 32);
;     for (int it = gw; it < DEPTH * (I1 + I2); it += NGW) {
;         if (it < DEPTH * I1) { const int l = it / I1, r = it % I1; transpose_item(a.in[4] + (size_t)l * DM * NCOLS, a.in[3] + l * DM, DM, NCOLS, W1T + (size_t)l * NCOLS * DM, 0, scr, r, lane, true); }
;         else { const int r2 = it - DEPTH * I1, l = r2 / I2, r = r2 % I2; transpose_item(a.in[12] + (size_t)l * MIXW * DM, nullptr, MIXW, DM, W2T + (size_t)l * DM * MIXW, 1024, scr, r, lane, false); }
;     }
.Lp0_again:
	s_mov_b64 s[24:25], s[90:91]
	v_mov_b32_e32 v7, v168
	s_load_dwordx2 s[14:15], s[24:25], 0x78
	v_readfirstlane_b32 s0, v7
	s_ashr_i32 s4, s0, 6
	s_load_dword s0, s[90:91], 0x88
	s_add_u32 s12, s90, 0x88
	s_addc_u32 s13, s91, 0
	s_lshl_b32 s1, s2, 3
	s_add_i32 s20, s4, s1
	s_waitcnt lgkmcnt(0)
	s_lshl_b32 s22, s0, 3
	s_cmpk_gt_i32 s20, 0x47ff
	v_and_b32_e32 v18, 63, v7
	s_cbranch_scc1 .LBB0_45
	s_add_u32 s1, s14, 0x800000
	s_addc_u32 s3, s15, 0
	s_add_u32 s18, s14, 0x4000000
	v_lshlrev_b32_e32 v1, 3, v18
	s_addc_u32 s21, s15, 0
	s_lshl_b32 s4, s4, 14
	v_lshrrev_b32_e32 v13, 3, v18
	v_and_b32_e32 v4, 56, v1
	s_add_i32 s5, s4, 0
	v_lshrrev_b32_e32 v6, 5, v18
	v_mul_u32_u24_e32 v1, 0x84, v4
	v_lshlrev_b32_e32 v3, 2, v13
	v_and_b32_e32 v2, 31, v7
	v_add3_u32 v19, s5, v1, v3
	v_mul_u32_u24_e32 v3, 0x84, v6
	v_mov_b32_e32 v9, 0
	v_lshlrev_b32_e32 v10, 2, v2
	v_or_b32_e32 v3, s4, v3
	s_mov_b32 s9, 0
	v_add_u32_e32 v12, s5, v10
	s_movk_i32 s23, 0x84
	v_or_b32_e32 v38, 8, v13
	v_or_b32_e32 v39, 16, v13
	v_or_b32_e32 v40, 24, v13
	v_bfe_u32 v41, v18, 3, 2
	v_mov_b32_e32 v1, v6
	v_add3_u32 v42, v3, v10, 0
	v_mov_b32_e32 v11, v9
	v_or_b32_e32 v43, 14, v6
	v_or_b32_e32 v44, 12, v6
	v_or_b32_e32 v45, 10, v6
	v_or_b32_e32 v46, 8, v6
	v_or_b32_e32 v47, 6, v6
	v_or_b32_e32 v48, 4, v6
	v_or_b32_e32 v49, 2, v6
	v_lshlrev_b32_e32 v14, 2, v2
	s_movk_i32 s30, 0x7000
	s_movk_i32 s31, 0x1000
	v_lshlrev_b32_e32 v16, 1, v4
	s_mov_b32 s33, s20
	s_branch .LBB0_14

; __global__ void __launch_bounds__(NWAVES * 64) fwd_kernel(Args a_) {
;     ...
;     if (ph == 0 && ph < ph_hi) {
;         { KArgs ap = ap0; asm volatile("" : "+s"(ap)); const Args& a = *(const Args*)ap; MK_TID; p0_prologue(a, lds, tid, lane, wave); }
;         ++ph;
.LBB0_85:
	s_cmp_eq_u32 s101, 0
	s_cbranch_scc0 .Lp0_done
	s_mov_b32 s101, 1
	s_branch .Lp0_again
